# v56 + SSD causal C.B^T blocks: B-fragment LDS reads of a block issued up front with counted waits
# speedup vs baseline: 1.0030x; 1.0030x over previous
; #define LAS __attribute__((address_space(3)))
; __device__ __forceinline__ unsigned cvt_pk_bf16(float lo, float hi) { unsigned r; asm volatile("v_cvt_pk_bf16_f32 %0, %1, %2" : "=v"(r) : "v"(lo), "v"(hi)); return r; }
; __device__ __forceinline__ void ssd_phase(const bf16_t* XBC, const float* DT  , const ss_t* SSq, const float* dtb, const bf16_t* Z, const float* a_log, const float* d_skip, bf16_t* YS, LAS unsigned char* lds, int tid, int wid, int lane, int bid, int G) {
;     ...
;             const int lrow = 16 * wid + fr; const float csl = csv[lrow];
;             bf16x8 Cfr[4];
; #pragma unroll
;             for (int ks = 0; ks < 4; ++ks) Cfr[ks] = *(const LAS bf16x8*)(Ct + lrow * SS_RS + 32 * ks + 8 * fq);
;             unsigned gp[8][2];
; #pragma unroll
;             for (int t = 0; t < 8; ++t) {
;                 if (t <= wid) {
;                     f32x4 acc = (f32x4){0.f, 0.f, 0.f, 0.f};
; #pragma unroll
;                     for (int ks = 0; ks < 4; ++ks) { const bf16x8 bfr = *(const LAS bf16x8*)(Bt + (16 * t + fr) * SS_RS + 32 * ks + 8 * fq); acc = __builtin_amdgcn_mfma_f32_16x16x32_bf16(bfr, Cfr[ks], acc, 0, 0, 0); }
;                     const f32x4 cs4 = *(const LAS f32x4*)(csv + 16 * t + 4 * fq); float v[4];
; #pragma unroll
;                     for (int r = 0; r < 4; ++r) { const int sx = 16 * t + 4 * fq + r; v[r] = (sx <= lrow) ? acc[r] * __expf(csl - cs4[r]) : 0.f; }
;                     gp[t][0] = cvt_pk_bf16(v[0], v[1]); gp[t][1] = cvt_pk_bf16(v[2], v[3]);
;                 } else { gp[t][0] = 0u; gp[t][1] = 0u; }
.LBB0_106:
	v_lshl_add_u32 v1, v110, 2, s30
	ds_read_b32 v131, v1
	ds_read_b128 v[86:89], v111
	ds_read_b128 v[82:85], v111 offset:64
	ds_read_b128 v[78:81], v111 offset:128
	ds_read_b128 v[74:77], v111 offset:192
	v_cndmask_b32_e64 v1, 0, 1, s[94:95]
	v_lshl_add_u32 v90, v165, 2, s30
	v_cmp_ne_u32_e64 s[84:85], 1, v1
	s_andn2_b64 vcc, exec, s[94:95]
	v_add_u32_e32 v91, v164, v168
	s_cbranch_vccnz .LBB0_108
	ds_read_b128 v[2:5], v91 offset:34816
	ds_read_b128 v[6:9], v91 offset:34880
	ds_read_b128 v[240:243], v91 offset:34944
	ds_read_b128 v[244:247], v91 offset:35008
	v_readlane_b32 s30, v255, 15
	v_readlane_b32 s31, v255, 16
	s_waitcnt lgkmcnt(3)
	v_mfma_f32_16x16x32_bf16 v[2:5], v[2:5], v[86:89], 0
	s_waitcnt lgkmcnt(2)
	v_mfma_f32_16x16x32_bf16 v[2:5], v[6:9], v[82:85], v[2:5]
	ds_read_b128 v[6:9], v90
	s_waitcnt lgkmcnt(2)
	v_mfma_f32_16x16x32_bf16 v[2:5], v[240:243], v[78:81], v[2:5]
	s_waitcnt lgkmcnt(1)
	v_mfma_f32_16x16x32_bf16 v[2:5], v[244:247], v[74:77], v[2:5]
	s_nop 1
	s_waitcnt lgkmcnt(0)
	v_sub_f32_e32 v1, v131, v6
	v_mul_f32_e32 v1, 0x3fb8aa3b, v1
	v_exp_f32_e32 v1, v1
	s_nop 2
	v_mul_f32_e32 v1, v2, v1
	v_sub_f32_e32 v2, v131, v7
	v_mul_f32_e32 v2, 0x3fb8aa3b, v2
	v_exp_f32_e32 v2, v2
	v_cndmask_b32_e64 v1, v1, 0, s[30:31]
	v_readlane_b32 s30, v255, 17
	v_readlane_b32 s31, v255, 18
	v_mul_f32_e32 v2, v3, v2
	v_sub_f32_e32 v3, v131, v8
	v_mul_f32_e32 v3, 0x3fb8aa3b, v3
	v_exp_f32_e32 v3, v3
	v_cndmask_b32_e64 v2, 0, v2, s[30:31]
	v_readlane_b32 s30, v255, 19
	v_readlane_b32 s31, v255, 20
	v_mul_f32_e32 v3, v4, v3
	v_sub_f32_e32 v4, v131, v9
	v_mul_f32_e32 v4, 0x3fb8aa3b, v4
	v_exp_f32_e32 v4, v4
	v_cndmask_b32_e64 v3, v3, 0, s[30:31]
	v_readlane_b32 s30, v255, 21
	v_readlane_b32 s31, v255, 22
	v_mul_f32_e32 v4, v5, v4
	v_cvt_pk_bf16_f32 v2, v1, v2
	s_nop 0
	v_cndmask_b32_e64 v4, v4, 0, s[30:31]
	s_mov_b64 s[30:31], 0
	v_cvt_pk_bf16_f32 v3, v3, v4
	s_branch .LBB0_109

; #define LAS __attribute__((address_space(3)))
; __device__ __forceinline__ unsigned cvt_pk_bf16(float lo, float hi) { unsigned r; asm volatile("v_cvt_pk_bf16_f32 %0, %1, %2" : "=v"(r) : "v"(lo), "v"(hi)); return r; }
; __device__ __forceinline__ void ssd_phase(const bf16_t* XBC, const float* DT  , const ss_t* SSq, const float* dtb, const bf16_t* Z, const float* a_log, const float* d_skip, bf16_t* YS, LAS unsigned char* lds, int tid, int wid, int lane, int bid, int G) {
;     ...
;                 if (t <= wid) {
;                     f32x4 acc = (f32x4){0.f, 0.f, 0.f, 0.f};
; #pragma unroll
;                     for (int ks = 0; ks < 4; ++ks) { const bf16x8 bfr = *(const LAS bf16x8*)(Bt + (16 * t + fr) * SS_RS + 32 * ks + 8 * fq); acc = __builtin_amdgcn_mfma_f32_16x16x32_bf16(bfr, Cfr[ks], acc, 0, 0, 0); }
;                     const f32x4 cs4 = *(const LAS f32x4*)(csv + 16 * t + 4 * fq); float v[4];
; #pragma unroll
;                     for (int r = 0; r < 4; ++r) { const int sx = 16 * t + 4 * fq + r; v[r] = (sx <= lrow) ? acc[r] * __expf(csl - cs4[r]) : 0.f; }
;                     gp[t][0] = cvt_pk_bf16(v[0], v[1]); gp[t][1] = cvt_pk_bf16(v[2], v[3]);
;                 } else { gp[t][0] = 0u; gp[t][1] = 0u; }
.LBB0_109:
	s_andn2_b64 vcc, exec, s[30:31]
	s_andn2_b64 vcc, exec, s[92:93]
	s_mov_b64 s[86:87], -1
	s_cbranch_vccnz .LBB0_111
	ds_read_b128 v[4:7], v91 offset:39168
	ds_read_b128 v[8:11], v91 offset:39232
	ds_read_b128 v[240:243], v91 offset:39296
	ds_read_b128 v[244:247], v91 offset:39360
	v_readlane_b32 s30, v255, 23
	v_readlane_b32 s31, v255, 24
	s_mov_b64 s[86:87], 0
	s_waitcnt lgkmcnt(3)
	v_mfma_f32_16x16x32_bf16 v[4:7], v[4:7], v[86:89], 0
	s_waitcnt lgkmcnt(2)
	v_mfma_f32_16x16x32_bf16 v[4:7], v[8:11], v[82:85], v[4:7]
	ds_read_b128 v[8:11], v90 offset:64
	s_waitcnt lgkmcnt(2)
	v_mfma_f32_16x16x32_bf16 v[4:7], v[240:243], v[78:81], v[4:7]
	s_waitcnt lgkmcnt(1)
	v_mfma_f32_16x16x32_bf16 v[4:7], v[244:247], v[74:77], v[4:7]
	s_nop 1
	s_waitcnt lgkmcnt(0)
	v_sub_f32_e32 v1, v131, v8
	v_mul_f32_e32 v1, 0x3fb8aa3b, v1
	v_exp_f32_e32 v1, v1
	s_nop 2
	v_mul_f32_e32 v1, v4, v1
	v_sub_f32_e32 v4, v131, v9
	v_mul_f32_e32 v4, 0x3fb8aa3b, v4
	v_exp_f32_e32 v4, v4
	v_cndmask_b32_e64 v1, v1, 0, s[30:31]
	v_readlane_b32 s30, v255, 25
	v_readlane_b32 s31, v255, 26
	v_mul_f32_e32 v4, v5, v4
	v_sub_f32_e32 v5, v131, v10
	v_mul_f32_e32 v5, 0x3fb8aa3b, v5
	v_exp_f32_e32 v5, v5
	v_cndmask_b32_e64 v4, v4, 0, s[30:31]
	v_readlane_b32 s30, v255, 27
	v_readlane_b32 s31, v255, 28
	v_mul_f32_e32 v5, v6, v5
	v_sub_f32_e32 v6, v131, v11
	v_mul_f32_e32 v6, 0x3fb8aa3b, v6
	v_exp_f32_e32 v6, v6
	v_cndmask_b32_e64 v5, v5, 0, s[30:31]
	v_readlane_b32 s30, v255, 29
	v_readlane_b32 s31, v255, 30
	v_mul_f32_e32 v6, v7, v6
	v_cvt_pk_bf16_f32 v4, v1, v4
	s_nop 0
	v_cndmask_b32_e64 v6, v6, 0, s[30:31]
	v_cvt_pk_bf16_f32 v5, v5, v6

; #define LAS __attribute__((address_space(3)))
; __device__ __forceinline__ unsigned cvt_pk_bf16(float lo, float hi) { unsigned r; asm volatile("v_cvt_pk_bf16_f32 %0, %1, %2" : "=v"(r) : "v"(lo), "v"(hi)); return r; }
; __device__ __forceinline__ void ssd_phase(const bf16_t* XBC, const float* DT  , const ss_t* SSq, const float* dtb, const bf16_t* Z, const float* a_log, const float* d_skip, bf16_t* YS, LAS unsigned char* lds, int tid, int wid, int lane, int bid, int G) {
;     ...
;                 if (t <= wid) {
;                     f32x4 acc = (f32x4){0.f, 0.f, 0.f, 0.f};
; #pragma unroll
;                     for (int ks = 0; ks < 4; ++ks) { const bf16x8 bfr = *(const LAS bf16x8*)(Bt + (16 * t + fr) * SS_RS + 32 * ks + 8 * fq); acc = __builtin_amdgcn_mfma_f32_16x16x32_bf16(bfr, Cfr[ks], acc, 0, 0, 0); }
;                     const f32x4 cs4 = *(const LAS f32x4*)(csv + 16 * t + 4 * fq); float v[4];
; #pragma unroll
;                     for (int r = 0; r < 4; ++r) { const int sx = 16 * t + 4 * fq + r; v[r] = (sx <= lrow) ? acc[r] * __expf(csl - cs4[r]) : 0.f; }
;                     gp[t][0] = cvt_pk_bf16(v[0], v[1]); gp[t][1] = cvt_pk_bf16(v[2], v[3]);
;                 } else { gp[t][0] = 0u; gp[t][1] = 0u; }
.LBB0_113:
	v_cndmask_b32_e64 v1, 0, 1, s[18:19]
	v_cmp_ne_u32_e64 s[86:87], 1, v1
	s_andn2_b64 vcc, exec, s[18:19]
	s_mov_b64 s[88:89], -1
	s_cbranch_vccnz .LBB0_115
	ds_read_b128 v[6:9], v91 offset:43520
	ds_read_b128 v[10:13], v91 offset:43584
	ds_read_b128 v[240:243], v91 offset:43648
	ds_read_b128 v[244:247], v91 offset:43712
	v_readlane_b32 s30, v255, 31
	v_readlane_b32 s31, v255, 32
	s_mov_b64 s[88:89], 0
	s_waitcnt lgkmcnt(3)
	v_mfma_f32_16x16x32_bf16 v[6:9], v[6:9], v[86:89], 0
	s_waitcnt lgkmcnt(2)
	v_mfma_f32_16x16x32_bf16 v[6:9], v[10:13], v[82:85], v[6:9]
	ds_read_b128 v[10:13], v90 offset:128
	s_waitcnt lgkmcnt(2)
	v_mfma_f32_16x16x32_bf16 v[6:9], v[240:243], v[78:81], v[6:9]
	s_waitcnt lgkmcnt(1)
	v_mfma_f32_16x16x32_bf16 v[6:9], v[244:247], v[74:77], v[6:9]
	s_nop 1
	s_waitcnt lgkmcnt(0)
	v_sub_f32_e32 v1, v131, v10
	v_mul_f32_e32 v1, 0x3fb8aa3b, v1
	v_exp_f32_e32 v1, v1
	s_nop 2
	v_mul_f32_e32 v1, v6, v1
	v_sub_f32_e32 v6, v131, v11
	v_mul_f32_e32 v6, 0x3fb8aa3b, v6
	v_exp_f32_e32 v6, v6
	v_cndmask_b32_e64 v1, v1, 0, s[30:31]
	v_readlane_b32 s30, v255, 33
	v_readlane_b32 s31, v255, 34
	v_mul_f32_e32 v6, v7, v6
	v_sub_f32_e32 v7, v131, v12
	v_mul_f32_e32 v7, 0x3fb8aa3b, v7
	v_exp_f32_e32 v7, v7
	v_cndmask_b32_e64 v6, v6, 0, s[30:31]
	v_cvt_pk_bf16_f32 v12, v1, v6
	v_mul_f32_e32 v7, v8, v7
	v_sub_f32_e32 v8, v131, v13
	v_mul_f32_e32 v8, 0x3fb8aa3b, v8
	v_exp_f32_e32 v8, v8
	v_cndmask_b32_e64 v7, v7, 0, s[40:41]
	v_mul_f32_e32 v8, v9, v8
	v_cndmask_b32_e64 v8, v8, 0, s[42:43]
	v_cvt_pk_bf16_f32 v13, v7, v8

; #define LAS __attribute__((address_space(3)))
; __device__ __forceinline__ unsigned cvt_pk_bf16(float lo, float hi) { unsigned r; asm volatile("v_cvt_pk_bf16_f32 %0, %1, %2" : "=v"(r) : "v"(lo), "v"(hi)); return r; }
; __device__ __forceinline__ void ssd_phase(const bf16_t* XBC, const float* DT  , const ss_t* SSq, const float* dtb, const bf16_t* Z, const float* a_log, const float* d_skip, bf16_t* YS, LAS unsigned char* lds, int tid, int wid, int lane, int bid, int G) {
;     ...
;                 if (t <= wid) {
;                     f32x4 acc = (f32x4){0.f, 0.f, 0.f, 0.f};
; #pragma unroll
;                     for (int ks = 0; ks < 4; ++ks) { const bf16x8 bfr = *(const LAS bf16x8*)(Bt + (16 * t + fr) * SS_RS + 32 * ks + 8 * fq); acc = __builtin_amdgcn_mfma_f32_16x16x32_bf16(bfr, Cfr[ks], acc, 0, 0, 0); }
;                     const f32x4 cs4 = *(const LAS f32x4*)(csv + 16 * t + 4 * fq); float v[4];
; #pragma unroll
;                     for (int r = 0; r < 4; ++r) { const int sx = 16 * t + 4 * fq + r; v[r] = (sx <= lrow) ? acc[r] * __expf(csl - cs4[r]) : 0.f; }
;                     gp[t][0] = cvt_pk_bf16(v[0], v[1]); gp[t][1] = cvt_pk_bf16(v[2], v[3]);
;                 } else { gp[t][0] = 0u; gp[t][1] = 0u; }
.LBB0_117:
	s_andn2_b64 vcc, exec, s[20:21]
	s_mov_b64 s[30:31], -1
	s_cbranch_vccnz .LBB0_119
	v_add_u32_e32 v1, v164, v169
	ds_read_b128 v[6:9], v1 offset:34816
	ds_read_b128 v[14:17], v1 offset:34880
	ds_read_b128 v[240:243], v1 offset:34944
	ds_read_b128 v[244:247], v1 offset:35008
	s_mov_b64 s[30:31], 0
	s_waitcnt lgkmcnt(3)
	v_mfma_f32_16x16x32_bf16 v[6:9], v[6:9], v[86:89], 0
	s_waitcnt lgkmcnt(2)
	v_mfma_f32_16x16x32_bf16 v[6:9], v[14:17], v[82:85], v[6:9]
	ds_read_b128 v[14:17], v90 offset:192
	s_waitcnt lgkmcnt(2)
	v_mfma_f32_16x16x32_bf16 v[6:9], v[240:243], v[78:81], v[6:9]
	s_waitcnt lgkmcnt(1)
	v_mfma_f32_16x16x32_bf16 v[6:9], v[244:247], v[74:77], v[6:9]
	s_nop 1
	s_waitcnt lgkmcnt(0)
	v_sub_f32_e32 v1, v131, v14
	v_mul_f32_e32 v1, 0x3fb8aa3b, v1
	v_exp_f32_e32 v1, v1
	s_nop 2
	v_mul_f32_e32 v1, v6, v1
	v_sub_f32_e32 v6, v131, v15
	v_mul_f32_e32 v6, 0x3fb8aa3b, v6
	v_exp_f32_e32 v6, v6
	v_cndmask_b32_e64 v1, v1, 0, s[44:45]
	v_mul_f32_e32 v6, v7, v6
	v_sub_f32_e32 v7, v131, v16
	v_mul_f32_e32 v7, 0x3fb8aa3b, v7
	v_exp_f32_e32 v7, v7
	v_cndmask_b32_e64 v6, v6, 0, s[46:47]
	v_cvt_pk_bf16_f32 v14, v1, v6
	v_mul_f32_e32 v7, v8, v7
	v_sub_f32_e32 v8, v131, v17
	v_mul_f32_e32 v8, 0x3fb8aa3b, v8
	v_exp_f32_e32 v8, v8
	v_cndmask_b32_e64 v7, v7, 0, s[48:49]
	v_mul_f32_e32 v8, v9, v8
	v_cndmask_b32_e64 v8, v8, 0, s[50:51]
	v_cvt_pk_bf16_f32 v15, v7, v8

; #define LAS __attribute__((address_space(3)))
; __device__ __forceinline__ unsigned cvt_pk_bf16(float lo, float hi) { unsigned r; asm volatile("v_cvt_pk_bf16_f32 %0, %1, %2" : "=v"(r) : "v"(lo), "v"(hi)); return r; }
; __device__ __forceinline__ void ssd_phase(const bf16_t* XBC, const float* DT  , const ss_t* SSq, const float* dtb, const bf16_t* Z, const float* a_log, const float* d_skip, bf16_t* YS, LAS unsigned char* lds, int tid, int wid, int lane, int bid, int G) {
;     ...
;                 if (t <= wid) {
;                     f32x4 acc = (f32x4){0.f, 0.f, 0.f, 0.f};
; #pragma unroll
;                     for (int ks = 0; ks < 4; ++ks) { const bf16x8 bfr = *(const LAS bf16x8*)(Bt + (16 * t + fr) * SS_RS + 32 * ks + 8 * fq); acc = __builtin_amdgcn_mfma_f32_16x16x32_bf16(bfr, Cfr[ks], acc, 0, 0, 0); }
;                     const f32x4 cs4 = *(const LAS f32x4*)(csv + 16 * t + 4 * fq); float v[4];
; #pragma unroll
;                     for (int r = 0; r < 4; ++r) { const int sx = 16 * t + 4 * fq + r; v[r] = (sx <= lrow) ? acc[r] * __expf(csl - cs4[r]) : 0.f; }
;                     gp[t][0] = cvt_pk_bf16(v[0], v[1]); gp[t][1] = cvt_pk_bf16(v[2], v[3]);
;                 } else { gp[t][0] = 0u; gp[t][1] = 0u; }
.LBB0_121:
	v_cndmask_b32_e64 v1, 0, 1, s[22:23]
	v_cmp_ne_u32_e64 s[88:89], 1, v1
	s_andn2_b64 vcc, exec, s[22:23]
	s_mov_b64 s[90:91], -1
	s_cbranch_vccnz .LBB0_123
	ds_read_b128 v[6:9], v91 offset:52224
	ds_read_b128 v[92:95], v91 offset:52288
	ds_read_b128 v[240:243], v91 offset:52352
	ds_read_b128 v[244:247], v91 offset:52416
	s_mov_b64 s[90:91], 0
	s_waitcnt lgkmcnt(3)
	v_mfma_f32_16x16x32_bf16 v[6:9], v[6:9], v[86:89], 0
	s_waitcnt lgkmcnt(2)
	v_mfma_f32_16x16x32_bf16 v[6:9], v[92:95], v[82:85], v[6:9]
	ds_read_b128 v[92:95], v90 offset:256
	s_waitcnt lgkmcnt(2)
	v_mfma_f32_16x16x32_bf16 v[6:9], v[240:243], v[78:81], v[6:9]
	s_waitcnt lgkmcnt(1)
	v_mfma_f32_16x16x32_bf16 v[6:9], v[244:247], v[74:77], v[6:9]
	s_nop 1
	s_waitcnt lgkmcnt(0)
	v_sub_f32_e32 v1, v131, v92
	v_mul_f32_e32 v1, 0x3fb8aa3b, v1
	v_exp_f32_e32 v1, v1
	s_nop 2
	v_mul_f32_e32 v1, v6, v1
	v_sub_f32_e32 v6, v131, v93
	v_mul_f32_e32 v6, 0x3fb8aa3b, v6
	v_exp_f32_e32 v6, v6
	v_cndmask_b32_e64 v1, v1, 0, s[52:53]
	v_mul_f32_e32 v6, v7, v6
	v_sub_f32_e32 v7, v131, v94
	v_mul_f32_e32 v7, 0x3fb8aa3b, v7
	v_exp_f32_e32 v7, v7
	v_cndmask_b32_e64 v6, v6, 0, s[54:55]
	v_cvt_pk_bf16_f32 v94, v1, v6
	v_mul_f32_e32 v7, v8, v7
	v_sub_f32_e32 v8, v131, v95
	v_mul_f32_e32 v8, 0x3fb8aa3b, v8
	v_exp_f32_e32 v8, v8
	v_cndmask_b32_e64 v7, v7, 0, s[56:57]
	v_mul_f32_e32 v8, v9, v8
	v_cndmask_b32_e64 v8, v8, 0, s[58:59]
	v_cvt_pk_bf16_f32 v95, v7, v8

; #define LAS __attribute__((address_space(3)))
; __device__ __forceinline__ unsigned cvt_pk_bf16(float lo, float hi) { unsigned r; asm volatile("v_cvt_pk_bf16_f32 %0, %1, %2" : "=v"(r) : "v"(lo), "v"(hi)); return r; }
; __device__ __forceinline__ void ssd_phase(const bf16_t* XBC, const float* DT  , const ss_t* SSq, const float* dtb, const bf16_t* Z, const float* a_log, const float* d_skip, bf16_t* YS, LAS unsigned char* lds, int tid, int wid, int lane, int bid, int G) {
;     ...
;                 if (t <= wid) {
;                     f32x4 acc = (f32x4){0.f, 0.f, 0.f, 0.f};
; #pragma unroll
;                     for (int ks = 0; ks < 4; ++ks) { const bf16x8 bfr = *(const LAS bf16x8*)(Bt + (16 * t + fr) * SS_RS + 32 * ks + 8 * fq); acc = __builtin_amdgcn_mfma_f32_16x16x32_bf16(bfr, Cfr[ks], acc, 0, 0, 0); }
;                     const f32x4 cs4 = *(const LAS f32x4*)(csv + 16 * t + 4 * fq); float v[4];
; #pragma unroll
;                     for (int r = 0; r < 4; ++r) { const int sx = 16 * t + 4 * fq + r; v[r] = (sx <= lrow) ? acc[r] * __expf(csl - cs4[r]) : 0.f; }
;                     gp[t][0] = cvt_pk_bf16(v[0], v[1]); gp[t][1] = cvt_pk_bf16(v[2], v[3]);
;                 } else { gp[t][0] = 0u; gp[t][1] = 0u; }
.LBB0_125:
	s_andn2_b64 vcc, exec, s[24:25]
	s_mov_b64 s[30:31], -1
	s_cbranch_vccnz .LBB0_127
	ds_read_b128 v[6:9], v91 offset:56576
	ds_read_b128 v[96:99], v91 offset:56640
	ds_read_b128 v[240:243], v91 offset:56704
	ds_read_b128 v[244:247], v91 offset:56768
	s_mov_b64 s[30:31], 0
	s_waitcnt lgkmcnt(3)
	v_mfma_f32_16x16x32_bf16 v[6:9], v[6:9], v[86:89], 0
	s_waitcnt lgkmcnt(2)
	v_mfma_f32_16x16x32_bf16 v[6:9], v[96:99], v[82:85], v[6:9]
	ds_read_b128 v[96:99], v90 offset:320
	s_waitcnt lgkmcnt(2)
	v_mfma_f32_16x16x32_bf16 v[6:9], v[240:243], v[78:81], v[6:9]
	s_waitcnt lgkmcnt(1)
	v_mfma_f32_16x16x32_bf16 v[6:9], v[244:247], v[74:77], v[6:9]
	s_nop 1
	s_waitcnt lgkmcnt(0)
	v_sub_f32_e32 v1, v131, v96
	v_mul_f32_e32 v1, 0x3fb8aa3b, v1
	v_exp_f32_e32 v1, v1
	s_nop 2
	v_mul_f32_e32 v1, v6, v1
	v_sub_f32_e32 v6, v131, v97
	v_mul_f32_e32 v6, 0x3fb8aa3b, v6
	v_exp_f32_e32 v6, v6
	v_cndmask_b32_e64 v1, v1, 0, s[60:61]
	v_mul_f32_e32 v6, v7, v6
	v_sub_f32_e32 v7, v131, v98
	v_mul_f32_e32 v7, 0x3fb8aa3b, v7
	v_exp_f32_e32 v7, v7
	v_cndmask_b32_e64 v6, v6, 0, s[62:63]
	v_cvt_pk_bf16_f32 v96, v1, v6
	v_mul_f32_e32 v7, v8, v7
	v_sub_f32_e32 v8, v131, v99
	v_mul_f32_e32 v8, 0x3fb8aa3b, v8
	v_exp_f32_e32 v8, v8
	v_cndmask_b32_e64 v7, v7, 0, s[64:65]
	v_mul_f32_e32 v8, v9, v8
	v_cndmask_b32_e64 v8, v8, 0, s[66:67]
	v_cvt_pk_bf16_f32 v97, v7, v8

; #define LAS __attribute__((address_space(3)))
; __device__ __forceinline__ unsigned cvt_pk_bf16(float lo, float hi) { unsigned r; asm volatile("v_cvt_pk_bf16_f32 %0, %1, %2" : "=v"(r) : "v"(lo), "v"(hi)); return r; }
; __device__ __forceinline__ void ssd_phase(const bf16_t* XBC, const float* DT  , const ss_t* SSq, const float* dtb, const bf16_t* Z, const float* a_log, const float* d_skip, bf16_t* YS, LAS unsigned char* lds, int tid, int wid, int lane, int bid, int G) {
;     ...
;                 if (t <= wid) {
;                     f32x4 acc = (f32x4){0.f, 0.f, 0.f, 0.f};
; #pragma unroll
;                     for (int ks = 0; ks < 4; ++ks) { const bf16x8 bfr = *(const LAS bf16x8*)(Bt + (16 * t + fr) * SS_RS + 32 * ks + 8 * fq); acc = __builtin_amdgcn_mfma_f32_16x16x32_bf16(bfr, Cfr[ks], acc, 0, 0, 0); }
;                     const f32x4 cs4 = *(const LAS f32x4*)(csv + 16 * t + 4 * fq); float v[4];
; #pragma unroll
;                     for (int r = 0; r < 4; ++r) { const int sx = 16 * t + 4 * fq + r; v[r] = (sx <= lrow) ? acc[r] * __expf(csl - cs4[r]) : 0.f; }
;                     gp[t][0] = cvt_pk_bf16(v[0], v[1]); gp[t][1] = cvt_pk_bf16(v[2], v[3]);
;                 } else { gp[t][0] = 0u; gp[t][1] = 0u; }
.LBB0_129:
	v_cndmask_b32_e64 v1, 0, 1, s[26:27]
	v_cmp_ne_u32_e64 s[90:91], 1, v1
	s_andn2_b64 vcc, exec, s[26:27]
	s_mov_b64 s[30:31], -1
	s_cbranch_vccnz .LBB0_131
	ds_read_b128 v[6:9], v91 offset:60928
	ds_read_b128 v[98:101], v91 offset:60992
	ds_read_b128 v[240:243], v91 offset:61056
	ds_read_b128 v[244:247], v91 offset:61120
	s_mov_b64 s[30:31], 0
	s_waitcnt lgkmcnt(3)
	v_mfma_f32_16x16x32_bf16 v[6:9], v[6:9], v[86:89], 0
	s_waitcnt lgkmcnt(2)
	v_mfma_f32_16x16x32_bf16 v[6:9], v[98:101], v[82:85], v[6:9]
	ds_read_b128 v[98:101], v90 offset:384
	s_waitcnt lgkmcnt(2)
	v_mfma_f32_16x16x32_bf16 v[6:9], v[240:243], v[78:81], v[6:9]
	s_waitcnt lgkmcnt(1)
	v_mfma_f32_16x16x32_bf16 v[6:9], v[244:247], v[74:77], v[6:9]
	s_nop 1
	s_waitcnt lgkmcnt(0)
	v_sub_f32_e32 v1, v131, v98
	v_mul_f32_e32 v1, 0x3fb8aa3b, v1
	v_exp_f32_e32 v1, v1
	s_nop 2
	v_mul_f32_e32 v1, v6, v1
	v_sub_f32_e32 v6, v131, v99
	v_mul_f32_e32 v6, 0x3fb8aa3b, v6
	v_exp_f32_e32 v6, v6
	v_cndmask_b32_e64 v1, v1, 0, s[68:69]
	v_mul_f32_e32 v6, v7, v6
	v_sub_f32_e32 v7, v131, v100
	v_mul_f32_e32 v7, 0x3fb8aa3b, v7
	v_exp_f32_e32 v7, v7
	v_cndmask_b32_e64 v6, v6, 0, s[70:71]
	v_cvt_pk_bf16_f32 v98, v1, v6
	v_mul_f32_e32 v7, v8, v7
	v_sub_f32_e32 v8, v131, v101
	v_mul_f32_e32 v8, 0x3fb8aa3b, v8
	v_exp_f32_e32 v8, v8
	v_cndmask_b32_e64 v7, v7, 0, s[72:73]
	v_mul_f32_e32 v8, v9, v8
	v_cndmask_b32_e64 v8, v8, 0, s[74:75]
	v_cvt_pk_bf16_f32 v99, v7, v8
